# grid barrier: last cross-XCD arriver releases all per-XCD generation words directly (no TOPGEN->leader->XGEN hop), on top of early buffer_inv
# speedup vs baseline: 1.0054x; 1.0054x over previous
.LBB0_198:
	s_or_b64 exec, exec, s[2:3]
	v_mov_b32_e32 v2, s28
	v_add_co_u32_e32 v2, vcc, 0x2000, v2
	v_mov_b32_e32 v3, s25
	s_nop 0
	v_addc_co_u32_e32 v3, vcc, 0, v3, vcc
	s_waitcnt vmcnt(0) lgkmcnt(0)
	s_waitcnt vmcnt(0)

.LBB0_273:
	s_or_b64 exec, exec, s[8:9]
	s_and_saveexec_b64 s[2:3], s[10:11]
	s_cbranch_execz .LBB0_275
	flat_atomic_add v[2:3], v207
	v_add_co_u32_e32 v4, vcc, 0xffffef00, v2
	s_nop 1
	v_addc_co_u32_e32 v5, vcc, -1, v3, vcc
	flat_atomic_add v[4:5], v207
	flat_atomic_add v[4:5], v207 offset:256
	flat_atomic_add v[4:5], v207 offset:512
	flat_atomic_add v[4:5], v207 offset:768
	flat_atomic_add v[4:5], v207 offset:1024
	flat_atomic_add v[4:5], v207 offset:1280
	flat_atomic_add v[4:5], v207 offset:1536
	flat_atomic_add v[4:5], v207 offset:1792
	flat_atomic_add v[4:5], v207 offset:2048
	flat_atomic_add v[4:5], v207 offset:2304
	flat_atomic_add v[4:5], v207 offset:2560
	flat_atomic_add v[4:5], v207 offset:2816
	flat_atomic_add v[4:5], v207 offset:3072
	flat_atomic_add v[4:5], v207 offset:3328
	flat_atomic_add v[4:5], v207 offset:3584
	flat_atomic_add v[4:5], v207 offset:3840
.LBB0_275:
	s_or_b64 exec, exec, s[2:3]
	v_mov_b32_e32 v2, s38
	v_add_co_u32_e32 v2, vcc, 0x2000, v2
	v_mov_b32_e32 v3, s28
	s_nop 0
	v_addc_co_u32_e32 v3, vcc, 0, v3, vcc
	s_waitcnt vmcnt(0) lgkmcnt(0)
	s_waitcnt vmcnt(0)

.LBB0_1390:
	s_or_b64 exec, exec, s[6:7]
	s_and_saveexec_b64 s[2:3], s[8:9]
	s_cbranch_execz .LBB0_1392
	flat_atomic_add v[2:3], v207
	v_add_co_u32_e32 v4, vcc, 0xffffef00, v2
	s_nop 1
	v_addc_co_u32_e32 v5, vcc, -1, v3, vcc
	flat_atomic_add v[4:5], v207
	flat_atomic_add v[4:5], v207 offset:256
	flat_atomic_add v[4:5], v207 offset:512
	flat_atomic_add v[4:5], v207 offset:768
	flat_atomic_add v[4:5], v207 offset:1024
	flat_atomic_add v[4:5], v207 offset:1280
	flat_atomic_add v[4:5], v207 offset:1536
	flat_atomic_add v[4:5], v207 offset:1792
	flat_atomic_add v[4:5], v207 offset:2048
	flat_atomic_add v[4:5], v207 offset:2304
	flat_atomic_add v[4:5], v207 offset:2560
	flat_atomic_add v[4:5], v207 offset:2816
	flat_atomic_add v[4:5], v207 offset:3072
	flat_atomic_add v[4:5], v207 offset:3328
	flat_atomic_add v[4:5], v207 offset:3584
	flat_atomic_add v[4:5], v207 offset:3840
.LBB0_1392:
	s_or_b64 exec, exec, s[2:3]
	v_mov_b32_e32 v2, s36
	v_add_co_u32_e32 v2, vcc, 0x2000, v2
	v_mov_b32_e32 v3, s28
	s_nop 0
	v_addc_co_u32_e32 v3, vcc, 0, v3, vcc
	s_waitcnt vmcnt(0) lgkmcnt(0)
	s_waitcnt vmcnt(0)

.LBB0_1822:
	flat_atomic_add v[2:3], v207
	v_add_co_u32_e32 v4, vcc, 0xffffef00, v2
	s_nop 1
	v_addc_co_u32_e32 v5, vcc, -1, v3, vcc
	flat_atomic_add v[4:5], v207
	flat_atomic_add v[4:5], v207 offset:256
	flat_atomic_add v[4:5], v207 offset:512
	flat_atomic_add v[4:5], v207 offset:768
	flat_atomic_add v[4:5], v207 offset:1024
	flat_atomic_add v[4:5], v207 offset:1280
	flat_atomic_add v[4:5], v207 offset:1536
	flat_atomic_add v[4:5], v207 offset:1792
	flat_atomic_add v[4:5], v207 offset:2048
	flat_atomic_add v[4:5], v207 offset:2304
	flat_atomic_add v[4:5], v207 offset:2560
	flat_atomic_add v[4:5], v207 offset:2816
	flat_atomic_add v[4:5], v207 offset:3072
	flat_atomic_add v[4:5], v207 offset:3328
	flat_atomic_add v[4:5], v207 offset:3584
	flat_atomic_add v[4:5], v207 offset:3840
	s_getpc_b64 s[98:99]
